# queue-reorder+fox-pk-adds+xconv-4loads
# speedup vs baseline: 1.0285x; 1.0285x over previous
.LBB0_36:
	s_or_b64 exec, exec, s[10:11]
	s_mov_b64 s[10:11], src_shared_base
	s_xor_b64 s[40:41], s[66:67], -1
	s_xor_b64 s[44:45], s[20:21], -1
	s_add_i32 s10, 0, 0x20200
	s_cmp_lg_u32 s10, -1
	s_cselect_b32 s10, s10, 0
	s_cselect_b32 s11, s11, 0
	v_mov_b32_e32 v2, s10
	s_waitcnt lgkmcnt(0)
	v_mov_b32_e32 v3, s11
	s_waitcnt lgkmcnt(0)
	s_barrier
	flat_load_dword v0, v[2:3] sc0 sc1
	s_waitcnt vmcnt(0)
	s_mov_b64 s[38:39], -1
	s_waitcnt lgkmcnt(0)
	v_cmp_gt_i32_e32 vcc, s69, v0
	s_and_saveexec_b64 s[10:11], vcc
	s_cbranch_execz .LBB0_31
	s_cmpk_eq_i32 s69, 0x340
	s_cselect_b32 s18, 0x48, 0
	v_cmp_lt_u32_e32 vcc, 0xff, v0
	v_mov_b32_e32 v2, s18
	s_nop 0
	v_cndmask_b32_e32 v2, 0, v2, vcc
	v_add_u32_e32 v0, v0, v2
	v_mov_b32_e32 v2, 0xffffff78
	v_mov_b32_e32 v3, 0x1b8
	v_cmp_gt_u32_e32 vcc, 0x188, v0
	s_nop 1
	v_cndmask_b32_e32 v2, v2, v3, vcc
	v_mov_b32_e32 v3, 0x240
	v_cmp_gt_u32_e32 vcc, 0x148, v0
	s_nop 1
	v_cndmask_b32_e32 v2, v2, v3, vcc
	v_cmp_gt_u32_e32 vcc, 0x100, v0
	s_nop 1
	v_cndmask_b32_e64 v2, v2, 0, vcc
	v_add_u32_e32 v0, v0, v2
	s_movk_i32 s18, 0x340
	v_cmp_gt_i32_e32 vcc, s18, v0
	s_and_saveexec_b64 s[38:39], vcc
	s_xor_b64 s[38:39], exec, s[38:39]
	v_writelane_b32 v250, s38, 35
	s_nop 1
	v_writelane_b32 v250, s39, 36
	s_cbranch_execz .LBB0_259
	s_movk_i32 s18, 0x260
	v_add_u32_e32 v2, 0xfffffea0, v0
	v_cmp_gt_i32_e32 vcc, s18, v0
	s_movk_i32 s18, 0x1a0
	s_mov_b64 s[42:43], 0
	v_cndmask_b32_e32 v3, v218, v219, vcc
	v_cmp_gt_u32_e32 vcc, s18, v2
	s_movk_i32 s18, 0x1ff
	s_nop 0
	v_cndmask_b32_e32 v2, 0, v3, vcc
	v_add_u32_e32 v2, v2, v0
	v_cmp_lt_i32_e64 s[38:39], s18, v2
	s_and_saveexec_b64 s[18:19], s[38:39]
	s_xor_b64 s[18:19], exec, s[18:19]
	s_cbranch_execz .LBB0_57
	s_and_saveexec_b64 s[24:25], s[44:45]
	s_cbranch_execz .LBB0_56
	s_and_saveexec_b64 s[42:43], s[36:37]
	s_cbranch_execz .LBB0_55
	v_readlane_b32 s44, v252, 2
	v_readlane_b32 s45, v252, 3
	s_load_dword s34, s[44:45], 0x10
	s_load_dword s46, s[44:45], 0x0
	s_waitcnt lgkmcnt(0)
	s_lshr_b32 s34, s34, 16
	s_cmp_lg_u32 s34, 0
	s_cselect_b64 s[44:45], -1, 0
	s_cmp_lg_u64 s[44:45], 0
	s_addc_u32 s34, s46, 0
	s_mov_b32 s46, 0x1000000
	s_branch .LBB0_44

.LBB0_245:
	s_or_b64 exec, exec, s[38:39]
	s_mul_hi_u32 s38, s34, 0xaaaaaaab
	s_lshr_b32 s38, s38, 2
	s_mul_i32 s38, s38, 0x18000
	v_subrev_u32_e32 v6, 63, v141
	v_add_u32_e32 v0, 1, v139
	v_subrev_u32_e32 v144, s38, v131
	v_subrev_u32_e32 v145, s38, v132
	v_subrev_u32_e32 v146, s38, v133
	v_subrev_u32_e32 v147, s38, v134
	v_subrev_u32_e32 v2, s38, v130
	v_subrev_u32_e32 v3, s38, v129
	v_subrev_u32_e32 v4, s38, v127
	v_subrev_u32_e32 v5, s38, v126
	v_cmp_le_i32_e32 vcc, s34, v122
	v_cmp_le_i32_e64 s[38:39], v6, v125
	s_and_b64 s[38:39], vcc, s[38:39]
	v_cmp_ge_i32_e32 vcc, v0, v124
	v_add_u32_e32 v0, s49, v138
	s_and_b64 s[46:47], s[38:39], vcc
	v_add_u32_e32 v149, 0, v140
	v_add_u32_e32 v150, v0, v5
	v_add_u32_e32 v151, v0, v4
	v_add_u32_e32 v152, v0, v3
	v_add_u32_e32 v153, v0, v2
	s_and_saveexec_b64 s[38:39], s[46:47]
	s_cbranch_execz .LBB0_251
	ds_read_b128 v[2:5], v153 offset:20480
	ds_read_b128 v[6:9], v153 offset:16384
	ds_read_b128 v[10:13], v152 offset:20480
	ds_read_b128 v[154:157], v152 offset:16384
	ds_read_b128 v[158:161], v151 offset:20480
	ds_read_b128 v[162:165], v151 offset:16384
	ds_read_b128 v[166:169], v150 offset:20480
	ds_read_b128 v[80:83], v150 offset:16384
	ds_read_b128 v[84:87], v149 offset:432
	ds_read_b128 v[88:91], v149 offset:416
	ds_read_b128 v[184:187], v149 offset:400
	ds_read_b128 v[188:191], v149 offset:384
	ds_read_b128 v[64:67], v149 offset:256
	ds_read_b128 v[68:71], v149 offset:272
	ds_read_b128 v[72:75], v149 offset:288
	ds_read_b128 v[76:79], v149 offset:304
	s_waitcnt lgkmcnt(8)
	s_waitcnt lgkmcnt(0)
	s_setprio 1
	v_pk_add_f32 v[78:79], v[62:63], v[78:79] neg_lo:[0,1] neg_hi:[0,1]
	v_pk_add_f32 v[76:77], v[60:61], v[76:77] neg_lo:[0,1] neg_hi:[0,1]
	v_pk_add_f32 v[74:75], v[58:59], v[74:75] neg_lo:[0,1] neg_hi:[0,1]
	v_pk_add_f32 v[72:73], v[56:57], v[72:73] neg_lo:[0,1] neg_hi:[0,1]
	v_pk_add_f32 v[70:71], v[54:55], v[70:71] neg_lo:[0,1] neg_hi:[0,1]
	v_pk_add_f32 v[68:69], v[52:53], v[68:69] neg_lo:[0,1] neg_hi:[0,1]
	v_pk_add_f32 v[66:67], v[50:51], v[66:67] neg_lo:[0,1] neg_hi:[0,1]
	v_pk_add_f32 v[64:65], v[48:49], v[64:65] neg_lo:[0,1] neg_hi:[0,1]
	v_pk_add_f32 v[94:95], v[62:63], v[86:87] neg_lo:[0,1] neg_hi:[0,1]
	s_nop 0
	v_mfma_f32_32x32x16_bf16 v[64:79], v[80:83], v[96:99], v[64:79]
	v_pk_add_f32 v[92:93], v[60:61], v[84:85] neg_lo:[0,1] neg_hi:[0,1]
	v_pk_add_f32 v[90:91], v[58:59], v[90:91] neg_lo:[0,1] neg_hi:[0,1]
	v_pk_add_f32 v[88:89], v[56:57], v[88:89] neg_lo:[0,1] neg_hi:[0,1]
	v_pk_add_f32 v[86:87], v[54:55], v[186:187] neg_lo:[0,1] neg_hi:[0,1]
	v_pk_add_f32 v[84:85], v[52:53], v[184:185] neg_lo:[0,1] neg_hi:[0,1]
	v_pk_add_f32 v[82:83], v[50:51], v[190:191] neg_lo:[0,1] neg_hi:[0,1]
	v_pk_add_f32 v[80:81], v[48:49], v[188:189] neg_lo:[0,1] neg_hi:[0,1]
	v_mfma_f32_32x32x16_bf16 v[64:79], v[162:165], v[100:103], v[64:79]
	s_nop 0
	v_mfma_f32_32x32x16_bf16 v[80:95], v[166:169], v[96:99], v[80:95]
	v_mfma_f32_32x32x16_bf16 v[80:95], v[158:161], v[100:103], v[80:95]
	v_mfma_f32_32x32x16_bf16 v[64:79], v[154:157], v[104:107], v[64:79]
	v_mfma_f32_32x32x16_bf16 v[80:95], v[10:13], v[104:107], v[80:95]
	v_mfma_f32_32x32x16_bf16 v[64:79], v[6:9], v[108:111], v[64:79]
	v_mfma_f32_32x32x16_bf16 v[80:95], v[2:5], v[108:111], v[80:95]
	s_setprio 0
	s_nop 9
	v_exp_f32_e32 v165, v64
	v_exp_f32_e32 v164, v65
	v_exp_f32_e32 v163, v66
	v_exp_f32_e32 v162, v67
	v_exp_f32_e32 v161, v68
	v_exp_f32_e32 v160, v69
	v_exp_f32_e32 v159, v70
	v_exp_f32_e32 v158, v71
	v_exp_f32_e32 v157, v72
	v_exp_f32_e32 v156, v73
	v_exp_f32_e32 v155, v74
	v_exp_f32_e32 v154, v75
	v_exp_f32_e32 v76, v76
	v_exp_f32_e32 v75, v77
	v_exp_f32_e32 v74, v78
	v_exp_f32_e32 v72, v79
	v_exp_f32_e32 v0, v80
	v_exp_f32_e32 v11, v81
	v_exp_f32_e32 v10, v82
	v_exp_f32_e32 v13, v83
	v_exp_f32_e32 v12, v84
	v_exp_f32_e32 v15, v85
	v_exp_f32_e32 v14, v86
	v_exp_f32_e32 v65, v87
	v_exp_f32_e32 v64, v88
	v_exp_f32_e32 v67, v89
	v_exp_f32_e32 v66, v90
	v_exp_f32_e32 v69, v91
	v_exp_f32_e32 v68, v92
	v_exp_f32_e32 v71, v93
	v_exp_f32_e32 v70, v94
	v_exp_f32_e32 v73, v95
	v_cmp_le_i32_e32 vcc, v141, v115
	s_and_saveexec_b64 s[46:47], vcc
	s_xor_b64 s[46:47], exec, s[46:47]
	s_cbranch_execz .LBB0_248
	v_cvt_pk_bf16_f32 v9, v74, v72
	v_cvt_pk_bf16_f32 v2, v165, v164
	v_cvt_pk_bf16_f32 v3, v163, v162
	v_cvt_pk_bf16_f32 v4, v161, v160
	v_cvt_pk_bf16_f32 v5, v159, v158
	v_cvt_pk_bf16_f32 v6, v157, v156
	v_cvt_pk_bf16_f32 v7, v155, v154
	v_cvt_pk_bf16_f32 v8, v76, v75
	v_pk_add_f32 v[78:79], v[164:165], v[162:163]
	v_pk_add_f32 v[80:81], v[160:161], v[158:159]
	v_pk_add_f32 v[78:79], v[78:79], v[156:157]
	v_pk_add_f32 v[80:81], v[80:81], v[154:155]
	v_pk_add_f32 v[78:79], v[78:79], v[10:11]
	v_pk_add_f32 v[80:81], v[80:81], v[12:13]
	v_pk_add_f32 v[78:79], v[78:79], v[14:15]
	v_pk_add_f32 v[80:81], v[80:81], v[64:65]
	v_pk_add_f32 v[78:79], v[78:79], v[66:67]
	v_pk_add_f32 v[80:81], v[80:81], v[68:69]
	v_pk_add_f32 v[78:79], v[78:79], v[70:71]
	v_pk_add_f32 v[80:81], v[80:81], v[74:75]
	v_pk_add_f32 v[78:79], v[78:79], v[72:73]
	v_pk_add_f32 v[78:79], v[78:79], v[80:81]
	v_add_f32_e32 v78, v78, v79
	v_add_f32_e32 v78, v76, v78
	v_add_f32_e32 v78, v0, v78
	v_add_f32_e32 v148, v148, v78

.LBB0_251:
	s_or_b64 exec, exec, s[38:39]
	v_add_u32_e32 v0, 0xffffff81, v141
	v_cmp_lt_i32_e32 vcc, s34, v122
	v_cmp_le_i32_e64 s[38:39], v0, v125
	s_and_b64 s[38:39], vcc, s[38:39]
	v_cmp_ge_i32_e32 vcc, v139, v124
	s_and_b64 s[46:47], s[38:39], vcc
	s_and_saveexec_b64 s[38:39], s[46:47]
	s_cbranch_execz .LBB0_232
	ds_read_b128 v[2:5], v153 offset:36864
	ds_read_b128 v[6:9], v153 offset:32768
	ds_read_b128 v[10:13], v152 offset:36864
	ds_read_b128 v[152:155], v152 offset:32768
	ds_read_b128 v[156:159], v151 offset:36864
	ds_read_b128 v[160:163], v151 offset:32768
	ds_read_b128 v[164:167], v150 offset:36864
	ds_read_b128 v[80:83], v150 offset:32768
	ds_read_b128 v[84:87], v149 offset:176
	ds_read_b128 v[88:91], v149 offset:160
	ds_read_b128 v[184:187], v149 offset:144
	ds_read_b128 v[188:191], v149 offset:128
	ds_read_b128 v[64:67], v149
	ds_read_b128 v[68:71], v149 offset:16
	ds_read_b128 v[72:75], v149 offset:32
	ds_read_b128 v[76:79], v149 offset:48
	s_waitcnt lgkmcnt(8)
	s_waitcnt lgkmcnt(0)
	s_setprio 1
	v_pk_add_f32 v[78:79], v[62:63], v[78:79] neg_lo:[0,1] neg_hi:[0,1]
	v_pk_add_f32 v[76:77], v[60:61], v[76:77] neg_lo:[0,1] neg_hi:[0,1]
	v_pk_add_f32 v[74:75], v[58:59], v[74:75] neg_lo:[0,1] neg_hi:[0,1]
	v_pk_add_f32 v[72:73], v[56:57], v[72:73] neg_lo:[0,1] neg_hi:[0,1]
	v_pk_add_f32 v[70:71], v[54:55], v[70:71] neg_lo:[0,1] neg_hi:[0,1]
	v_pk_add_f32 v[68:69], v[52:53], v[68:69] neg_lo:[0,1] neg_hi:[0,1]
	v_pk_add_f32 v[66:67], v[50:51], v[66:67] neg_lo:[0,1] neg_hi:[0,1]
	v_pk_add_f32 v[64:65], v[48:49], v[64:65] neg_lo:[0,1] neg_hi:[0,1]
	v_pk_add_f32 v[94:95], v[62:63], v[86:87] neg_lo:[0,1] neg_hi:[0,1]
	s_nop 0
	v_mfma_f32_32x32x16_bf16 v[64:79], v[80:83], v[96:99], v[64:79]
	v_pk_add_f32 v[92:93], v[60:61], v[84:85] neg_lo:[0,1] neg_hi:[0,1]
	v_pk_add_f32 v[90:91], v[58:59], v[90:91] neg_lo:[0,1] neg_hi:[0,1]
	v_pk_add_f32 v[88:89], v[56:57], v[88:89] neg_lo:[0,1] neg_hi:[0,1]
	v_pk_add_f32 v[86:87], v[54:55], v[186:187] neg_lo:[0,1] neg_hi:[0,1]
	v_pk_add_f32 v[84:85], v[52:53], v[184:185] neg_lo:[0,1] neg_hi:[0,1]
	v_pk_add_f32 v[82:83], v[50:51], v[190:191] neg_lo:[0,1] neg_hi:[0,1]
	v_pk_add_f32 v[80:81], v[48:49], v[188:189] neg_lo:[0,1] neg_hi:[0,1]
	v_mfma_f32_32x32x16_bf16 v[64:79], v[160:163], v[100:103], v[64:79]
	s_nop 0
	v_mfma_f32_32x32x16_bf16 v[80:95], v[164:167], v[96:99], v[80:95]
	v_mfma_f32_32x32x16_bf16 v[80:95], v[156:159], v[100:103], v[80:95]
	v_mfma_f32_32x32x16_bf16 v[64:79], v[152:155], v[104:107], v[64:79]
	v_mfma_f32_32x32x16_bf16 v[80:95], v[10:13], v[104:107], v[80:95]
	v_mfma_f32_32x32x16_bf16 v[64:79], v[6:9], v[108:111], v[64:79]
	v_mfma_f32_32x32x16_bf16 v[80:95], v[2:5], v[108:111], v[80:95]
	s_setprio 0
	s_nop 9
	v_exp_f32_e32 v160, v64
	v_exp_f32_e32 v159, v65
	v_exp_f32_e32 v158, v66
	v_exp_f32_e32 v157, v67
	v_exp_f32_e32 v156, v68
	v_exp_f32_e32 v155, v69
	v_exp_f32_e32 v154, v70
	v_exp_f32_e32 v153, v71
	v_exp_f32_e32 v152, v72
	v_exp_f32_e32 v151, v73
	v_exp_f32_e32 v150, v74
	v_exp_f32_e32 v149, v75
	v_exp_f32_e32 v76, v76
	v_exp_f32_e32 v75, v77
	v_exp_f32_e32 v74, v78
	v_exp_f32_e32 v72, v79
	v_exp_f32_e32 v0, v80
	v_exp_f32_e32 v11, v81
	v_exp_f32_e32 v10, v82
	v_exp_f32_e32 v13, v83
	v_exp_f32_e32 v12, v84
	v_exp_f32_e32 v15, v85
	v_exp_f32_e32 v14, v86
	v_exp_f32_e32 v65, v87
	v_exp_f32_e32 v64, v88
	v_exp_f32_e32 v67, v89
	v_exp_f32_e32 v66, v90
	v_exp_f32_e32 v69, v91
	v_exp_f32_e32 v68, v92
	v_exp_f32_e32 v71, v93
	v_exp_f32_e32 v70, v94
	v_exp_f32_e32 v73, v95
	v_subrev_u32_e32 v2, 64, v141
	v_cmp_le_i32_e32 vcc, v2, v115
	s_and_saveexec_b64 s[46:47], vcc
	s_xor_b64 s[46:47], exec, s[46:47]
	s_cbranch_execz .LBB0_254
	v_cvt_pk_bf16_f32 v9, v74, v72
	v_cvt_pk_bf16_f32 v2, v160, v159
	v_cvt_pk_bf16_f32 v3, v158, v157
	v_cvt_pk_bf16_f32 v4, v156, v155
	v_cvt_pk_bf16_f32 v5, v154, v153
	v_cvt_pk_bf16_f32 v6, v152, v151
	v_cvt_pk_bf16_f32 v7, v150, v149
	v_cvt_pk_bf16_f32 v8, v76, v75
	v_pk_add_f32 v[78:79], v[158:159], v[156:157]
	v_pk_add_f32 v[80:81], v[154:155], v[152:153]
	v_pk_add_f32 v[78:79], v[78:79], v[150:151]
	v_pk_add_f32 v[80:81], v[80:81], v[10:11]
	v_pk_add_f32 v[78:79], v[78:79], v[12:13]
	v_pk_add_f32 v[80:81], v[80:81], v[14:15]
	v_pk_add_f32 v[78:79], v[78:79], v[64:65]
	v_pk_add_f32 v[80:81], v[80:81], v[66:67]
	v_pk_add_f32 v[78:79], v[78:79], v[68:69]
	v_pk_add_f32 v[80:81], v[80:81], v[70:71]
	v_pk_add_f32 v[78:79], v[78:79], v[74:75]
	v_pk_add_f32 v[80:81], v[80:81], v[72:73]
	v_pk_add_f32 v[78:79], v[78:79], v[80:81]
	v_add_f32_e32 v78, v78, v79
	v_add_f32_e32 v78, v160, v78
	v_add_f32_e32 v78, v149, v78
	v_add_f32_e32 v78, v76, v78
	v_add_f32_e32 v78, v0, v78
	v_add_f32_e32 v148, v148, v78

.LBB0_972:
	v_ashrrev_i32_e32 v3, 31, v2
	s_waitcnt lgkmcnt(0)
	v_lshlrev_b64 v[16:17], 12, v[2:3]
	v_lshl_add_u64 v[28:29], v[8:9], 0, v[16:17]
	global_load_dwordx4 v[16:19], v[28:29], off
	global_load_dwordx4 v[20:23], v[28:29], off offset:1024
	global_load_dwordx4 v[24:27], v[28:29], off offset:2048
	global_load_dwordx4 v[28:31], v[28:29], off offset:3072
	v_lshlrev_b64 v[32:33], 11, v[2:3]
	v_lshl_add_u64 v[32:33], v[4:5], 0, v[32:33]
	s_waitcnt vmcnt(3)
	v_mul_f32_e32 v0, v17, v17
	v_fmac_f32_e32 v0, v16, v16
	v_fmac_f32_e32 v0, v18, v18
	v_fmac_f32_e32 v0, v19, v19
	v_cvt_pk_bf16_f32 v16, v16, v17
	v_cvt_pk_bf16_f32 v17, v18, v19
	global_store_dwordx2 v[32:33], v[16:17], off
	s_waitcnt vmcnt(3)
	v_mul_f32_e32 v18, v21, v21
	v_fmac_f32_e32 v18, v20, v20
	v_fmac_f32_e32 v18, v22, v22
	v_fmac_f32_e32 v18, v23, v23
	v_add_f32_e32 v0, v0, v18
	v_cvt_pk_bf16_f32 v20, v20, v21
	v_cvt_pk_bf16_f32 v21, v22, v23
	global_store_dwordx2 v[32:33], v[20:21], off offset:512
	s_waitcnt vmcnt(3)
	v_mul_f32_e32 v18, v25, v25
	v_fmac_f32_e32 v18, v24, v24
	v_fmac_f32_e32 v18, v26, v26
	v_fmac_f32_e32 v18, v27, v27
	v_add_f32_e32 v0, v0, v18
	v_cvt_pk_bf16_f32 v24, v24, v25
	v_cvt_pk_bf16_f32 v25, v26, v27
	global_store_dwordx2 v[32:33], v[24:25], off offset:1024
	s_waitcnt vmcnt(3)
	v_mul_f32_e32 v18, v29, v29
	v_fmac_f32_e32 v18, v28, v28
	v_fmac_f32_e32 v18, v30, v30
	v_fmac_f32_e32 v18, v31, v31
	v_add_f32_e32 v0, v0, v18
	v_cvt_pk_bf16_f32 v18, v28, v29
	v_cvt_pk_bf16_f32 v19, v30, v31
	global_store_dwordx2 v[32:33], v[18:19], off offset:1536
	ds_bpermute_b32 v16, v10, v0
	s_waitcnt lgkmcnt(0)
	v_add_f32_e32 v0, v0, v16
	ds_bpermute_b32 v16, v11, v0
	s_waitcnt lgkmcnt(0)
	v_add_f32_e32 v0, v0, v16
	ds_bpermute_b32 v16, v12, v0
	s_waitcnt lgkmcnt(0)
	v_add_f32_e32 v0, v0, v16
	ds_bpermute_b32 v16, v13, v0
	s_waitcnt lgkmcnt(0)
	v_add_f32_e32 v0, v0, v16
	ds_bpermute_b32 v16, v14, v0
	s_waitcnt lgkmcnt(0)
	v_add_f32_e32 v0, v0, v16
	ds_bpermute_b32 v16, v15, v0
	s_and_saveexec_b64 s[6:7], vcc
	s_cbranch_execz .LBB0_971
	s_waitcnt lgkmcnt(0)
	v_add_f32_e32 v0, v0, v16
	v_lshlrev_b64 v[16:17], 6, v[2:3]
	v_cndmask_b32_e64 v0, 0, v0, s[36:37]
	v_lshl_add_u64 v[16:17], v[6:7], 0, v[16:17]
	global_store_dword v[16:17], v0, off
	s_branch .LBB0_971
